# added static s_setprio 1 for waves 0-3 during dn_chunk_pre (on top of waves 4-7 raise in the work-queue phases)
# baseline (speedup 1.0000x reference)
.LBB0_404:
	s_or_b64 exec, exec, s[4:5]
	s_waitcnt lgkmcnt(0)
	s_barrier
	v_readfirstlane_b32 s4, v148
	s_lshr_b32 s4, s4, 6
	s_cmp_lt_u32 s4, 4
	s_cbranch_scc0 .Lprio_dc_skip
	s_setprio 1
.Lprio_dc_skip:
	s_mov_b32 s4, 0
	s_ashr_i32 s5, s4, 31
	v_readlane_b32 s6, v253, 3
	v_readlane_b32 s7, v253, 4
	s_add_u32 s4, s6, s4
	s_addc_u32 s5, s7, s5
	v_mov_b32 v33, v148
	s_load_dwordx2 s[4:5], s[4:5], 0x100
	s_waitcnt vmcnt(0)
	v_mov_b32_e32 v51, 0
	v_lshrrev_b32_e32 v46, 4, v33
	v_cmp_gt_u32_e64 s[42:43], 64, v33
	v_mov_b32_e32 v54, 0
	s_waitcnt lgkmcnt(0)
	s_add_u32 s84, s4, 0x25800000
	s_addc_u32 s85, s5, 0
	s_add_u32 s86, s4, 0x27000000
	s_addc_u32 s87, s5, 0
	s_add_u32 s6, s4, 0x28980000
	s_addc_u32 s7, s5, 0
	v_writelane_b32 v252, s6, 17
	s_nop 1
	v_writelane_b32 v252, s7, 18
	v_readlane_b32 s6, v254, 25
	v_readlane_b32 s7, v254, 26
	s_andn2_b64 vcc, exec, s[6:7]
	s_nop 0
	v_cndmask_b32_e64 v0, 0, 1, s[6:7]
	v_cmp_ne_u32_e64 s[40:41], 1, v0
	s_cbranch_vccnz .LBB0_408
	v_readlane_b32 s6, v254, 42
	v_readlane_b32 s30, v254, 38
	v_readlane_b32 s34, v254, 55
	v_or_b32_e32 v4, s6, v46
	v_readlane_b32 s6, v254, 40
	v_readlane_b32 s35, v254, 56
	s_mov_b32 s35, s89
	v_sub_u32_e32 v0, s6, v4
	v_readlane_b32 s6, v254, 27
	v_readlane_b32 s7, v254, 28
	v_lshlrev_b32_e32 v5, 4, v33
	v_and_b32_e32 v128, 0xf0, v5
	v_cndmask_b32_e64 v0, v0, v4, s[6:7]
	v_add_u32_e32 v0, s30, v0
	v_ashrrev_i32_e32 v1, 31, v0
	v_lshlrev_b64 v[0:1], 11, v[0:1]
	v_lshl_add_u64 v[2:3], s[84:85], 0, v[0:1]
	v_lshl_add_u64 v[0:1], s[86:87], 0, v[0:1]
	v_lshl_add_u64 v[2:3], v[2:3], 0, s[34:35]
	v_lshl_add_u64 v[0:1], v[0:1], 0, s[34:35]
	v_lshl_add_u64 v[2:3], v[2:3], 0, v[128:129]
	v_lshl_add_u64 v[0:1], v[0:1], 0, v[128:129]
	v_readlane_b32 s31, v254, 39
	global_load_dwordx4 v[16:19], v[2:3], off
	global_load_dwordx4 v[20:23], v[0:1], off
	v_sub_u32_e32 v0, s31, v4
	v_readlane_b32 s31, v254, 43
	v_mov_b32_e32 v54, 0
	v_mov_b32_e32 v51, 0
	v_or_b32_e32 v1, s31, v46
	v_cndmask_b32_e64 v0, v0, v1, s[6:7]
	v_add_u32_e32 v0, s30, v0
	v_ashrrev_i32_e32 v1, 31, v0
	v_lshlrev_b64 v[0:1], 11, v[0:1]
	v_lshl_add_u64 v[2:3], s[84:85], 0, v[0:1]
	v_lshl_add_u64 v[2:3], v[2:3], 0, s[34:35]
	v_lshl_add_u64 v[0:1], s[86:87], 0, v[0:1]
	v_lshl_add_u64 v[2:3], v[2:3], 0, v[128:129]
	v_lshl_add_u64 v[0:1], v[0:1], 0, s[34:35]
	v_lshl_add_u64 v[0:1], v[0:1], 0, v[128:129]
	global_load_dwordx4 v[24:27], v[2:3], off
	global_load_dwordx4 v[28:31], v[0:1], off
	s_mov_b32 s6, s34
	v_writelane_b32 v254, s6, 55
	s_nop 1
	v_writelane_b32 v254, s7, 56
	s_and_saveexec_b64 s[38:39], s[42:43]
	s_cbranch_execz .LBB0_407
	v_readlane_b32 s6, v254, 42
	s_nop 1
	v_or_b32_e32 v0, s6, v33
	v_readlane_b32 s6, v254, 40
	s_nop 1
	v_sub_u32_e32 v1, s6, v0
	v_readlane_b32 s6, v254, 27
	v_readlane_b32 s7, v254, 28
	s_nop 1
	v_cndmask_b32_e64 v0, v1, v0, s[6:7]
	v_readlane_b32 s6, v254, 38
	s_nop 1
	v_add_u32_e32 v0, s6, v0
	v_ashrrev_i32_e32 v1, 31, v0
	v_readlane_b32 s6, v252, 17
	v_lshlrev_b64 v[0:1], 7, v[0:1]
	v_readlane_b32 s7, v252, 18
	s_nop 1
	v_lshl_add_u64 v[0:1], s[6:7], 0, v[0:1]
	v_readlane_b32 s6, v254, 57
	s_mov_b32 s30, s6
	v_readlane_b32 s7, v254, 58
	v_writelane_b32 v254, s30, 57
	s_mov_b32 s7, s89
	v_lshl_add_u64 v[0:1], v[0:1], 0, s[6:7]
	v_writelane_b32 v254, s31, 58
	s_nop 0
	v_readlane_b32 s6, v254, 59
	v_readlane_b32 s7, v254, 60
	s_mov_b32 s7, s89
	s_mov_b32 s30, s6
	v_lshl_add_u64 v[0:1], v[0:1], 0, s[6:7]
	global_load_dword v54, v[0:1], off
	global_load_dword v51, v[0:1], off offset:64
	v_writelane_b32 v254, s30, 59
	s_nop 1
	v_writelane_b32 v254, s31, 60

.LBB0_646:
	s_or_b64 exec, exec, s[4:5]
	s_waitcnt lgkmcnt(0)
	s_barrier
	s_setprio 0
	v_readfirstlane_b32 s30, v148
	s_lshr_b32 s30, s30, 6
	s_cmp_ge_u32 s30, 4
	s_cbranch_scc0 .Lprio_q1_skip
	s_setprio 1
